# write-through (sc1) on the 16-byte stores of the weight-conversion tiles (less dirty L2 to flush at the following barrier)
# speedup vs baseline: 1.0085x; 1.0031x over previous
.LBB0_188:
	s_waitcnt lgkmcnt(0)
	v_cvt_pk_bf16_f32 v4, v7, v0
	v_cvt_pk_bf16_f32 v5, v6, v5
	v_cvt_pk_bf16_f32 v6, v9, v8
	v_cvt_pk_bf16_f32 v7, v11, v10
	global_store_dwordx4 v[2:3], v[4:7], off offset:384 sc1

.LBB0_249:
	v_ashrrev_i32_e32 v18, 31, v2
	s_waitcnt lgkmcnt(0)
	v_cvt_pk_bf16_f32 v14, v7, v3
	v_mad_u64_u32 v[2:3], s[12:13], v2, s33, 0
	v_cvt_pk_bf16_f32 v15, v9, v8
	v_mov_b32_e32 v8, v3
	s_mul_i32 s4, s70, s71
	v_mad_u64_u32 v[8:9], s[12:13], v18, s33, v[8:9]
	s_add_i32 s4, s69, s4
	v_mov_b32_e32 v3, v8
	s_ashr_i32 s5, s4, 31
	v_lshl_add_u64 v[2:3], v[2:3], 1, s[42:43]
	v_lshlrev_b32_e32 v6, 3, v0
	v_lshl_add_u64 v[2:3], s[4:5], 1, v[2:3]
	v_lshlrev_b32_e32 v0, 4, v0
	v_cvt_pk_bf16_f32 v16, v11, v10
	v_cvt_pk_bf16_f32 v17, v13, v12
	v_lshl_add_u64 v[2:3], v[2:3], 0, v[0:1]
	v_mov_b32_e32 v0, 0
	s_and_b64 vcc, exec, s[40:41]
	v_mov_b32_e32 v7, 0
	global_store_dwordx4 v[2:3], v[14:17], off sc1
	s_cbranch_vccnz .LBB0_257
	v_or_b32_e32 v7, 64, v6
	v_mad_u32_u24 v7, v7, s84, v5
	ds_read_b32 v7, v7
	s_and_b64 vcc, exec, s[40:41]
	s_cbranch_vccz .LBB0_258

.LBB0_265:
	s_waitcnt lgkmcnt(0)
	v_cvt_pk_bf16_f32 v14, v7, v0
	v_cvt_pk_bf16_f32 v15, v9, v8
	v_cvt_pk_bf16_f32 v16, v11, v10
	v_cvt_pk_bf16_f32 v17, v13, v12
	v_mov_b32_e32 v0, 0
	s_and_b64 vcc, exec, s[40:41]
	v_mov_b32_e32 v7, 0
	global_store_dwordx4 v[2:3], v[14:17], off offset:128 sc1
	s_cbranch_vccnz .LBB0_273
	v_or_b32_e32 v7, 0x80, v6
	v_mad_u32_u24 v7, v7, s84, v5
	ds_read_b32 v7, v7
	s_and_b64 vcc, exec, s[40:41]
	s_cbranch_vccz .LBB0_274

.LBB0_281:
	s_waitcnt lgkmcnt(0)
	v_cvt_pk_bf16_f32 v14, v7, v0
	v_cvt_pk_bf16_f32 v15, v9, v8
	v_cvt_pk_bf16_f32 v16, v11, v10
	v_cvt_pk_bf16_f32 v17, v13, v12
	v_mov_b32_e32 v0, 0
	s_and_b64 vcc, exec, s[40:41]
	v_mov_b32_e32 v7, 0
	global_store_dwordx4 v[2:3], v[14:17], off offset:256 sc1
	s_cbranch_vccnz .LBB0_289
	v_or_b32_e32 v6, 0xc0, v6
	v_mad_u32_u24 v5, v6, s84, v5
	ds_read_b32 v7, v5
	s_and_b64 vcc, exec, s[40:41]
	s_cbranch_vccz .LBB0_290

.LBB0_440:
	v_ashrrev_i32_e32 v18, 31, v2
	s_waitcnt lgkmcnt(0)
	v_cvt_pk_bf16_f32 v14, v7, v3
	v_mad_u64_u32 v[2:3], s[12:13], v2, s56, 0
	v_cvt_pk_bf16_f32 v15, v9, v8
	v_mov_b32_e32 v8, v3
	s_mul_i32 s4, s67, s68
	v_mad_u64_u32 v[8:9], s[12:13], v18, s56, v[8:9]
	s_add_i32 s4, s65, s4
	v_mov_b32_e32 v3, v8
	s_ashr_i32 s5, s4, 31
	v_lshl_add_u64 v[2:3], v[2:3], 1, s[42:43]
	v_lshlrev_b32_e32 v6, 3, v0
	v_lshl_add_u64 v[2:3], s[4:5], 1, v[2:3]
	v_lshlrev_b32_e32 v0, 4, v0
	v_cvt_pk_bf16_f32 v16, v11, v10
	v_cvt_pk_bf16_f32 v17, v13, v12
	v_lshl_add_u64 v[2:3], v[2:3], 0, v[0:1]
	v_mov_b32_e32 v0, 0
	s_and_b64 vcc, exec, s[40:41]
	v_mov_b32_e32 v7, 0
	global_store_dwordx4 v[2:3], v[14:17], off sc1
	s_cbranch_vccnz .LBB0_448
	v_or_b32_e32 v7, 64, v6
	v_mad_u32_u24 v7, v7, s84, v5
	ds_read_b32 v7, v7
	s_and_b64 vcc, exec, s[40:41]
	s_cbranch_vccz .LBB0_449

.LBB0_960:
	s_mulk_i32 s20, 0xf500
	s_add_i32 s14, s18, s20
	s_waitcnt lgkmcnt(0)
	v_cvt_pk_bf16_f32 v15, v9, v8
	v_mov_b64_e32 v[8:9], s[6:7]
	s_movk_i32 s20, 0x1600
	s_ashr_i32 s15, s14, 31
	v_mad_i64_i32 v[8:9], s[20:21], v0, s20, v[8:9]
	v_lshl_add_u64 v[8:9], s[14:15], 1, v[8:9]
	v_lshlrev_b32_e32 v0, 4, v2
	v_lshlrev_b32_e32 v6, 3, v2
	v_cvt_pk_bf16_f32 v14, v7, v3
	v_cvt_pk_bf16_f32 v16, v11, v10
	v_cvt_pk_bf16_f32 v17, v13, v12
	v_lshl_add_u64 v[2:3], v[8:9], 0, v[0:1]
	v_mov_b32_e32 v0, 0
	s_and_b64 vcc, exec, s[40:41]
	v_mov_b32_e32 v7, 0
	global_store_dwordx4 v[2:3], v[14:17], off sc1
	s_cbranch_vccnz .LBB0_968
	v_or_b32_e32 v7, 64, v6
	v_mad_u32_u24 v7, v7, s84, v5
	ds_read_b32 v7, v7
	s_and_b64 vcc, exec, s[40:41]
	s_cbranch_vccz .LBB0_969

.LBB0_1153:
	s_or_b64 exec, exec, s[18:19]
	v_ashrrev_i32_e32 v4, 3, v68
	v_add_u32_e32 v3, v4, v67
	v_cmp_lt_i32_e32 vcc, v3, v51
	s_waitcnt lgkmcnt(0)
	s_barrier
	s_and_saveexec_b64 s[18:19], vcc
	s_cbranch_execz .LBB0_1219
	v_and_b32_e32 v2, 7, v68
	v_lshl_add_u32 v5, v4, 2, 0
	s_movk_i32 s3, 0x820
	v_cmp_lt_i32_e32 vcc, -1, v0
	v_mov_b32_e32 v0, 0
	v_mad_u32_u24 v4, v2, s3, v5
	v_mov_b32_e32 v7, 0
	s_and_saveexec_b64 s[20:21], vcc
	ds_read_b32 v7, v4
	s_or_b64 exec, exec, s[20:21]
	s_and_saveexec_b64 s[20:21], vcc
	ds_read_b32 v0, v4 offset:260
	s_or_b64 exec, exec, s[20:21]
	v_mov_b32_e32 v8, 0
	v_mov_b32_e32 v9, 0
	s_and_saveexec_b64 s[20:21], vcc
	ds_read_b32 v9, v4 offset:520
	s_or_b64 exec, exec, s[20:21]
	s_and_saveexec_b64 s[20:21], vcc
	ds_read_b32 v8, v4 offset:780
	s_or_b64 exec, exec, s[20:21]
	v_mov_b32_e32 v10, 0
	v_mov_b32_e32 v11, 0
	s_and_saveexec_b64 s[20:21], vcc
	ds_read_b32 v11, v4 offset:1040
	s_or_b64 exec, exec, s[20:21]
	s_and_saveexec_b64 s[20:21], vcc
	ds_read_b32 v10, v4 offset:1300
	s_or_b64 exec, exec, s[20:21]
	v_mov_b32_e32 v12, 0
	v_mov_b32_e32 v13, 0
	s_and_saveexec_b64 s[20:21], vcc
	ds_read_b32 v13, v4 offset:1560
	s_or_b64 exec, exec, s[20:21]
	s_and_saveexec_b64 s[20:21], vcc
	ds_read_b32 v12, v4 offset:1820
	s_or_b64 exec, exec, s[20:21]
	s_waitcnt lgkmcnt(0)
	v_cvt_pk_bf16_f32 v15, v9, v8
	v_mad_u64_u32 v[8:9], s[12:13], v3, v66, 0
	v_ashrrev_i32_e32 v18, 31, v3
	v_cvt_pk_bf16_f32 v14, v7, v0
	v_mov_b32_e32 v0, v9
	v_cvt_pk_bf16_f32 v16, v11, v10
	v_mad_u64_u32 v[10:11], s[12:13], v18, v66, v[0:1]
	v_mov_b32_e32 v9, v10
	v_ashrrev_i32_e32 v51, 31, v50
	v_lshl_add_u64 v[8:9], v[8:9], 1, v[46:47]
	v_lshl_add_u64 v[8:9], v[50:51], 1, v[8:9]
	v_lshlrev_b32_e32 v0, 4, v2
	v_lshlrev_b32_e32 v6, 3, v2
	v_cvt_pk_bf16_f32 v17, v13, v12
	v_lshl_add_u64 v[2:3], v[8:9], 0, v[0:1]
	v_mov_b32_e32 v0, 0
	v_mov_b32_e32 v7, 0
	global_store_dwordx4 v[2:3], v[14:17], off sc1
	s_and_saveexec_b64 s[20:21], vcc
	v_or_b32_e32 v7, 64, v6
	v_mad_u32_u24 v7, v7, s84, v5
	ds_read_b32 v7, v7
	s_or_b64 exec, exec, s[20:21]
	s_and_saveexec_b64 s[20:21], vcc
	ds_read_b32 v0, v4 offset:16900
	s_or_b64 exec, exec, s[20:21]
	v_mov_b32_e32 v8, 0
	v_mov_b32_e32 v9, 0
	s_and_saveexec_b64 s[20:21], vcc
	ds_read_b32 v9, v4 offset:17160
	s_or_b64 exec, exec, s[20:21]
	s_and_saveexec_b64 s[20:21], vcc
	ds_read_b32 v8, v4 offset:17420
	s_or_b64 exec, exec, s[20:21]
	v_mov_b32_e32 v10, 0
	v_mov_b32_e32 v11, 0
	s_and_saveexec_b64 s[20:21], vcc
	ds_read_b32 v11, v4 offset:17680
	s_or_b64 exec, exec, s[20:21]
	s_and_saveexec_b64 s[20:21], vcc
	ds_read_b32 v10, v4 offset:17940
	s_or_b64 exec, exec, s[20:21]
	v_mov_b32_e32 v12, 0
	v_mov_b32_e32 v13, 0
	s_and_saveexec_b64 s[20:21], vcc
	ds_read_b32 v13, v4 offset:18200
	s_or_b64 exec, exec, s[20:21]
	s_and_saveexec_b64 s[20:21], vcc
	ds_read_b32 v12, v4 offset:18460
	s_or_b64 exec, exec, s[20:21]
	s_waitcnt lgkmcnt(0)
	v_cvt_pk_bf16_f32 v14, v7, v0
	v_cvt_pk_bf16_f32 v15, v9, v8
	v_cvt_pk_bf16_f32 v16, v11, v10
	v_cvt_pk_bf16_f32 v17, v13, v12
	v_mov_b32_e32 v0, 0
	v_mov_b32_e32 v7, 0
	global_store_dwordx4 v[2:3], v[14:17], off offset:128 sc1
	s_and_saveexec_b64 s[20:21], vcc
	v_or_b32_e32 v7, 0x80, v6
	v_mad_u32_u24 v7, v7, s84, v5
	ds_read_b32 v7, v7
	s_or_b64 exec, exec, s[20:21]
	s_and_saveexec_b64 s[20:21], vcc
	ds_read_b32 v0, v4 offset:33540
	s_or_b64 exec, exec, s[20:21]
	v_mov_b32_e32 v8, 0
	v_mov_b32_e32 v9, 0
	s_and_saveexec_b64 s[20:21], vcc
	ds_read_b32 v9, v4 offset:33800
	s_or_b64 exec, exec, s[20:21]
	s_and_saveexec_b64 s[20:21], vcc
	ds_read_b32 v8, v4 offset:34060
	s_or_b64 exec, exec, s[20:21]
	v_mov_b32_e32 v10, 0
	v_mov_b32_e32 v11, 0
	s_and_saveexec_b64 s[20:21], vcc
	ds_read_b32 v11, v4 offset:34320
	s_or_b64 exec, exec, s[20:21]
	s_and_saveexec_b64 s[20:21], vcc
	ds_read_b32 v10, v4 offset:34580
	s_or_b64 exec, exec, s[20:21]
	v_mov_b32_e32 v12, 0
	v_mov_b32_e32 v13, 0
	s_and_saveexec_b64 s[20:21], vcc
	ds_read_b32 v13, v4 offset:34840
	s_or_b64 exec, exec, s[20:21]
	s_and_saveexec_b64 s[20:21], vcc
	ds_read_b32 v12, v4 offset:35100
	s_or_b64 exec, exec, s[20:21]
	s_waitcnt lgkmcnt(0)
	v_cvt_pk_bf16_f32 v14, v7, v0
	v_cvt_pk_bf16_f32 v15, v9, v8
	v_cvt_pk_bf16_f32 v16, v11, v10
	v_cvt_pk_bf16_f32 v17, v13, v12
	v_mov_b32_e32 v0, 0
	v_mov_b32_e32 v7, 0
	global_store_dwordx4 v[2:3], v[14:17], off offset:256 sc1
	s_and_saveexec_b64 s[20:21], vcc
	v_or_b32_e32 v6, 0xc0, v6
	v_mad_u32_u24 v5, v6, s84, v5
	ds_read_b32 v7, v5
	s_or_b64 exec, exec, s[20:21]
	s_and_saveexec_b64 s[20:21], vcc
	ds_read_b32 v0, v4 offset:50180
	s_or_b64 exec, exec, s[20:21]
	v_mov_b32_e32 v5, 0
	v_mov_b32_e32 v6, 0
	s_and_saveexec_b64 s[20:21], vcc
	ds_read_b32 v6, v4 offset:50440
	s_or_b64 exec, exec, s[20:21]
	s_and_saveexec_b64 s[20:21], vcc
	ds_read_b32 v5, v4 offset:50700
	s_or_b64 exec, exec, s[20:21]
	v_mov_b32_e32 v8, 0
	v_mov_b32_e32 v9, 0
	s_and_saveexec_b64 s[20:21], vcc
	ds_read_b32 v9, v4 offset:50960
	s_or_b64 exec, exec, s[20:21]
	s_and_saveexec_b64 s[20:21], vcc
	ds_read_b32 v8, v4 offset:51220
	s_or_b64 exec, exec, s[20:21]
	v_mov_b32_e32 v10, 0
	v_mov_b32_e32 v11, 0
	s_and_saveexec_b64 s[20:21], vcc
	ds_read_b32 v11, v4 offset:51480
	s_or_b64 exec, exec, s[20:21]
	s_and_saveexec_b64 s[20:21], vcc
	ds_read_b32 v10, v4 offset:51740
	s_or_b64 exec, exec, s[20:21]
	s_waitcnt lgkmcnt(0)
	v_cvt_pk_bf16_f32 v4, v7, v0
	v_cvt_pk_bf16_f32 v5, v6, v5
	v_cvt_pk_bf16_f32 v6, v9, v8
	v_cvt_pk_bf16_f32 v7, v11, v10
	global_store_dwordx4 v[2:3], v[4:7], off offset:384 sc1
